# NORMKV head-partial reduce: 8 cndmask selects + 4 ds_swizzle SWAP16 + lgkm wait fused into 4 v_permlane16_swap + 4 adds
# speedup vs baseline: 1.0023x; 1.0023x over previous
.Lmy_nk_noreload:
	v_cvt_f32_f16_sdwa v43, v32 dst_sel:DWORD dst_unused:UNUSED_PAD src0_sel:WORD_1
	v_cvt_f32_f16_e32 v42, v32
	v_cvt_f32_f16_sdwa v41, v33 dst_sel:DWORD dst_unused:UNUSED_PAD src0_sel:WORD_1
	v_cvt_f32_f16_e32 v40, v33
	v_cvt_f32_f16_sdwa v45, v30 dst_sel:DWORD dst_unused:UNUSED_PAD src0_sel:WORD_1
	v_cvt_f32_f16_e32 v44, v30
	v_cvt_f32_f16_sdwa v47, v31 dst_sel:DWORD dst_unused:UNUSED_PAD src0_sel:WORD_1
	v_cvt_f32_f16_e32 v46, v31
	v_cvt_f32_f16_sdwa v37, v26 dst_sel:DWORD dst_unused:UNUSED_PAD src0_sel:WORD_1
	v_cvt_f32_f16_e32 v36, v26
	v_pk_mul_f32 v[32:33], v[42:43], v[42:43]
	v_pk_mul_f32 v[34:35], v[40:41], v[40:41]
	v_pk_mul_f32 v[48:49], v[44:45], v[44:45]
	v_pk_mul_f32 v[50:51], v[46:47], v[46:47]
	v_pk_mul_f32 v[52:53], v[36:37], v[36:37]
	v_add_f32_e32 v50, v50, v51
	v_add_f32_e32 v48, v48, v49
	v_add_f32_e32 v34, v34, v35
	v_add_f32_e32 v32, v32, v33
	v_add_f32_e32 v48, v48, v50
	v_add_f32_e32 v32, v32, v34
	v_add_f32_e32 v34, v52, v53
	v_cvt_f32_f16_sdwa v39, v27 dst_sel:DWORD dst_unused:UNUSED_PAD src0_sel:WORD_1
	v_cvt_f32_f16_e32 v38, v27
	v_cvt_f32_f16_sdwa v27, v28 dst_sel:DWORD dst_unused:UNUSED_PAD src0_sel:WORD_1
	v_cvt_f32_f16_e32 v26, v28
	v_cvt_f32_f16_sdwa v31, v29 dst_sel:DWORD dst_unused:UNUSED_PAD src0_sel:WORD_1
	v_cvt_f32_f16_e32 v30, v29
	v_pk_mul_f32 v[54:55], v[38:39], v[38:39]
	v_pk_mul_f32 v[28:29], v[26:27], v[26:27]
	v_add_f32_e32 v33, v54, v55
	v_pk_mul_f32 v[58:59], v[30:31], v[30:31]
	v_add_f32_e32 v32, v32, v48
	v_add_f32_e32 v33, v34, v33
	v_add_f32_e32 v32, v33, v32
	v_add_f32_e32 v33, v58, v59
	v_add_f32_e32 v28, v28, v29
	v_add_f32_e32 v28, v28, v33
	v_add_f32_e32 v28, v28, v32
	s_ashr_i32 s2, s50, 13
	v_mad_i64_i32 v[48:49], s[0:1], s2, v252, v[8:9]
	v_lshl_add_u64 v[34:35], s[52:53], 0, v[0:1]
	s_waitcnt lgkmcnt(0)
	s_nop 1
	v_add_f32_dpp v28, v28, v28 quad_perm:[1,0,3,2] row_mask:0xf bank_mask:0xf
	s_ashr_i32 s3, s2, 31
	s_waitcnt lgkmcnt(0)
	s_nop 1
	v_add_f32_dpp v28, v28, v28 quad_perm:[2,3,0,1] row_mask:0xf bank_mask:0xf
	s_waitcnt lgkmcnt(0)
	s_nop 1
	v_add_f32_dpp v28, v28, v28 row_half_mirror row_mask:0xf bank_mask:0xf
	s_waitcnt lgkmcnt(0)
	s_nop 1
	v_add_f32_dpp v28, v28, v28 row_mirror row_mask:0xf bank_mask:0xf
	v_mov_b32_e32 v29, v28
	s_nop 1
	v_permlane16_swap_b32_e32 v29, v28
	s_waitcnt lgkmcnt(0)
	v_add_f32_e32 v28, v28, v29
	v_mov_b32_e32 v29, v28
	s_nop 1
	v_permlane32_swap_b32_e32 v28, v29
	v_add_f32_e32 v28, v28, v29
	v_fmamk_f32 v28, v28, 0x3a800000, v244
	v_rsq_f32_e32 v32, v28
	v_mad_i64_i32 v[28:29], s[0:1], s2, v252, v[2:3]
	s_mov_b32 s0, 0x1b400000
	v_pk_mul_f32 v[40:41], v[40:41], v[32:33] op_sel_hi:[1,0]
	v_pk_mul_f32 v[42:43], v[42:43], v[32:33] op_sel_hi:[1,0]
	v_pk_mul_f32 v[46:47], v[46:47], v[32:33] op_sel_hi:[1,0]
	v_pk_mul_f32 v[44:45], v[44:45], v[32:33] op_sel_hi:[1,0]
	v_pk_mul_f32 v[38:39], v[38:39], v[32:33] op_sel_hi:[1,0]
	v_pk_mul_f32 v[36:37], v[36:37], v[32:33] op_sel_hi:[1,0]
	v_mov_b64_e32 v[50:51], v[100:101]
	v_mov_b64_e32 v[52:53], v[102:103]
	v_pk_mul_f32 v[54:55], v[50:51], v[42:43]
	v_pk_mul_f32 v[58:59], v[52:53], v[40:41]
	v_mov_b64_e32 v[50:51], v[104:105]
	v_mov_b64_e32 v[52:53], v[106:107]
	v_pk_add_f32 v[60:61], v[52:53], 1.0 op_sel_hi:[1,0]
	v_pk_add_f32 v[62:63], v[50:51], 1.0 op_sel_hi:[1,0]
	v_mov_b64_e32 v[50:51], v[108:109]
	v_mov_b64_e32 v[52:53], v[110:111]
	v_pk_fma_f32 v[50:51], v[62:63], v[54:55], v[50:51]
	v_add_co_u32_e32 v54, vcc, s0, v34
	v_pk_fma_f32 v[52:53], v[60:61], v[58:59], v[52:53]
	s_nop 0
	v_addc_co_u32_e32 v55, vcc, 0, v35, vcc
	v_cvt_pk_bf16_f32 v50, v50, v51
	v_cvt_pk_bf16_f32 v51, v52, v53
	global_store_dwordx2 v[54:55], v[50:51], off
	v_mov_b64_e32 v[50:51], v[112:113]
	v_mov_b64_e32 v[52:53], v[114:115]
	s_lshl_b64 s[0:1], s[2:3], 13
	v_pk_mul_f32 v[58:59], v[50:51], v[44:45]
	v_pk_mul_f32 v[60:61], v[52:53], v[46:47]
	v_mov_b64_e32 v[50:51], v[116:117]
	v_mov_b64_e32 v[52:53], v[118:119]
	v_pk_add_f32 v[62:63], v[52:53], 1.0 op_sel_hi:[1,0]
	v_pk_add_f32 v[64:65], v[50:51], 1.0 op_sel_hi:[1,0]
	v_mov_b64_e32 v[50:51], v[120:121]
	v_mov_b64_e32 v[52:53], v[122:123]
	v_pk_fma_f32 v[50:51], v[64:65], v[58:59], v[50:51]
	v_pk_fma_f32 v[52:53], v[62:63], v[60:61], v[52:53]
	v_cvt_pk_bf16_f32 v50, v50, v51
	s_nop 0
	v_cvt_pk_bf16_f32 v51, v52, v53
	global_store_dwordx2 v[54:55], v[50:51], off offset:512
	v_mov_b64_e32 v[50:51], v[124:125]
	v_mov_b64_e32 v[52:53], v[126:127]
	v_pk_mul_f32 v[58:59], v[36:37], v[50:51]
	v_pk_mul_f32 v[60:61], v[38:39], v[52:53]
	v_mov_b64_e32 v[50:51], v[128:129]
	v_mov_b64_e32 v[52:53], v[130:131]
	v_pk_add_f32 v[62:63], v[52:53], 1.0 op_sel_hi:[1,0]
	v_pk_add_f32 v[64:65], v[50:51], 1.0 op_sel_hi:[1,0]
	v_mov_b64_e32 v[50:51], v[132:133]
	v_mov_b64_e32 v[52:53], v[134:135]
	v_pk_fma_f32 v[50:51], v[58:59], v[64:65], v[50:51]
	v_pk_fma_f32 v[52:53], v[60:61], v[62:63], v[52:53]
	v_cvt_pk_bf16_f32 v50, v50, v51
	s_nop 0
	v_cvt_pk_bf16_f32 v51, v52, v53
	global_store_dwordx2 v[54:55], v[50:51], off offset:1024
	v_pk_mul_f32 v[50:51], v[30:31], v[32:33] op_sel_hi:[1,0]
	v_pk_mul_f32 v[52:53], v[26:27], v[32:33] op_sel_hi:[1,0]
	v_mov_b64_e32 v[30:31], v[136:137]
	v_mov_b64_e32 v[32:33], v[138:139]
	v_pk_mul_f32 v[58:59], v[52:53], v[30:31]
	v_pk_mul_f32 v[60:61], v[50:51], v[32:33]
	v_mov_b64_e32 v[30:31], v[140:141]
	v_mov_b64_e32 v[32:33], v[142:143]
	s_nop 0
	v_mov_b64_e32 v[26:27], v[144:145]
	v_mov_b64_e32 v[28:29], v[146:147]
	v_lshl_add_u64 v[48:49], v[4:5], 0, s[0:1]
	v_pk_add_f32 v[30:31], v[30:31], 1.0 op_sel_hi:[1,0]
	v_pk_add_f32 v[32:33], v[32:33], 1.0 op_sel_hi:[1,0]
	v_pk_fma_f32 v[26:27], v[58:59], v[30:31], v[26:27]
	v_pk_fma_f32 v[28:29], v[60:61], v[32:33], v[28:29]
	v_cvt_pk_bf16_f32 v26, v26, v27
	s_nop 0
	v_cvt_pk_bf16_f32 v27, v28, v29
	global_store_dwordx2 v[54:55], v[26:27], off offset:1536
	v_mov_b64_e32 v[26:27], v[148:149]
	v_mov_b64_e32 v[28:29], v[150:151]
	v_lshl_add_u64 v[54:55], v[10:11], 0, s[0:1]
	s_mov_b32 s0, 0x3400000
	v_pk_mul_f32 v[32:33], v[42:43], v[26:27]
	v_pk_mul_f32 v[40:41], v[40:41], v[28:29]
	v_mov_b64_e32 v[26:27], v[152:153]
	v_mov_b64_e32 v[28:29], v[154:155]
	v_pk_add_f32 v[42:43], v[28:29], 1.0 op_sel_hi:[1,0]
	v_mov_b64_e32 v[28:29], v[156:157]
	v_mov_b64_e32 v[30:31], v[158:159]
	v_pk_add_f32 v[58:59], v[26:27], 1.0 op_sel_hi:[1,0]
	v_pk_fma_f32 v[26:27], v[40:41], v[42:43], v[30:31]
	v_pk_fma_f32 v[28:29], v[32:33], v[58:59], v[28:29]
	v_add_co_u32_e32 v58, vcc, s0, v34
	v_cvt_pk_bf16_f32 v30, v28, v29
	v_cvt_pk_bf16_f32 v31, v26, v27
	s_nop 1
	v_addc_co_u32_e32 v59, vcc, 0, v35, vcc
	global_store_dwordx2 v[58:59], v[30:31], off
	v_mov_b64_e32 v[30:31], v[160:161]
	v_mov_b64_e32 v[32:33], v[162:163]
	v_pk_mul_f32 v[40:41], v[44:45], v[30:31]
	v_pk_mul_f32 v[42:43], v[46:47], v[32:33]
	v_mov_b64_e32 v[30:31], v[164:165]
	v_mov_b64_e32 v[32:33], v[166:167]
	v_pk_add_f32 v[44:45], v[32:33], 1.0 op_sel_hi:[1,0]
	v_mov_b64_e32 v[32:33], v[168:169]
	v_mov_b64_e32 v[34:35], v[170:171]
	v_pk_add_f32 v[46:47], v[30:31], 1.0 op_sel_hi:[1,0]
	v_pk_fma_f32 v[30:31], v[42:43], v[44:45], v[34:35]
	v_pk_fma_f32 v[32:33], v[40:41], v[46:47], v[32:33]
	s_nop 0
	v_cvt_pk_bf16_f32 v34, v32, v33
	v_cvt_pk_bf16_f32 v35, v30, v31
	global_store_dwordx2 v[58:59], v[34:35], off offset:512
	v_mov_b64_e32 v[40:41], v[172:173]
	v_mov_b64_e32 v[42:43], v[174:175]
	v_pk_mul_f32 v[40:41], v[36:37], v[40:41]
	v_mov_b64_e32 v[34:35], v[176:177]
	v_mov_b64_e32 v[36:37], v[178:179]
	v_pk_mul_f32 v[38:39], v[38:39], v[42:43]
	v_pk_add_f32 v[42:43], v[36:37], 1.0 op_sel_hi:[1,0]
	v_pk_add_f32 v[44:45], v[34:35], 1.0 op_sel_hi:[1,0]
	v_mov_b64_e32 v[34:35], v[180:181]
	v_mov_b64_e32 v[36:37], v[182:183]
	v_pk_fma_f32 v[38:39], v[38:39], v[42:43], v[36:37]
	v_pk_fma_f32 v[40:41], v[40:41], v[44:45], v[34:35]
	s_nop 0
	v_cvt_pk_bf16_f32 v34, v40, v41
	v_cvt_pk_bf16_f32 v35, v38, v39
	global_store_dwordx2 v[58:59], v[34:35], off offset:1024
	v_mov_b64_e32 v[34:35], v[184:185]
	v_mov_b64_e32 v[36:37], v[186:187]
	v_pk_mul_f32 v[46:47], v[52:53], v[34:35]
	v_pk_mul_f32 v[50:51], v[50:51], v[36:37]
	v_mov_b64_e32 v[34:35], v[188:189]
	v_mov_b64_e32 v[36:37], v[190:191]
	v_mov_b64_e32 v[42:43], v[192:193]
	v_mov_b64_e32 v[44:45], v[194:195]
	v_pk_add_f32 v[36:37], v[36:37], 1.0 op_sel_hi:[1,0]
	v_pk_add_f32 v[52:53], v[34:35], 1.0 op_sel_hi:[1,0]
	v_pk_fma_f32 v[34:35], v[50:51], v[36:37], v[44:45]
	v_pk_fma_f32 v[36:37], v[46:47], v[52:53], v[42:43]
	s_nop 0
	v_cvt_pk_bf16_f32 v42, v36, v37
	v_cvt_pk_bf16_f32 v43, v34, v35
	global_store_dwordx2 v[58:59], v[42:43], off offset:1536
	v_mbcnt_lo_u32_b32 v96, -1, 0
	v_mbcnt_hi_u32_b32 v96, -1, v96
	ds_read_b128 v[196:199], v56
	ds_read_b128 v[200:203], v56 offset:1024
	ds_read_b128 v[204:207], v56 offset:2048
	ds_read_b128 v[208:211], v56 offset:3072
	ds_read_b128 v[212:215], v56 offset:4096
	ds_read_b128 v[216:219], v56 offset:5120
	ds_read_b128 v[220:223], v56 offset:6144
	ds_read_b128 v[224:227], v56 offset:7168
	v_lshrrev_b32_e32 v97, 2, v96
	v_and_b32_e32 v98, 3, v96
	v_lshl_or_b32 v97, v97, 4, v98
	v_and_b32_e32 v97, 63, v97
	v_lshlrev_b32_e32 v97, 2, v97
	s_waitcnt lgkmcnt(4)
	v_mul_f32_e32 v228, v29, v197
	v_mul_f32_e32 v229, v27, v199
	v_mul_f32_e32 v230, v33, v201
	v_mul_f32_e32 v231, v31, v203
	v_mul_f32_e32 v232, v41, v205
	v_mul_f32_e32 v233, v39, v207
	v_mul_f32_e32 v234, v37, v209
	v_mul_f32_e32 v235, v35, v211
	v_fmac_f32_e32 v228, v28, v196
	v_fmac_f32_e32 v229, v26, v198
	v_fmac_f32_e32 v230, v32, v200
	v_fmac_f32_e32 v231, v30, v202
	v_fmac_f32_e32 v232, v40, v204
	v_fmac_f32_e32 v233, v38, v206
	v_fmac_f32_e32 v234, v36, v208
	v_fmac_f32_e32 v235, v34, v210
	v_add_f32_e32 v228, v228, v229
	v_add_f32_e32 v230, v230, v231
	v_add_f32_e32 v232, v232, v233
	v_add_f32_e32 v234, v234, v235
	v_add_f32_e32 v80, 0, v228
	v_add_f32_e32 v80, v80, v230
	v_add_f32_e32 v80, v80, v232
	v_add_f32_e32 v80, v80, v234
	ds_read_b128 v[196:199], v56 offset:8192
	ds_read_b128 v[200:203], v56 offset:9216
	ds_read_b128 v[204:207], v56 offset:10240
	ds_read_b128 v[208:211], v56 offset:11264
	s_waitcnt lgkmcnt(4)
	v_mul_f32_e32 v228, v29, v213
	v_mul_f32_e32 v229, v27, v215
	v_mul_f32_e32 v230, v33, v217
	v_mul_f32_e32 v231, v31, v219
	v_mul_f32_e32 v232, v41, v221
	v_mul_f32_e32 v233, v39, v223
	v_mul_f32_e32 v234, v37, v225
	v_mul_f32_e32 v235, v35, v227
	v_fmac_f32_e32 v228, v28, v212
	v_fmac_f32_e32 v229, v26, v214
	v_fmac_f32_e32 v230, v32, v216
	v_fmac_f32_e32 v231, v30, v218
	v_fmac_f32_e32 v232, v40, v220
	v_fmac_f32_e32 v233, v38, v222
	v_fmac_f32_e32 v234, v36, v224
	v_fmac_f32_e32 v235, v34, v226
	v_add_f32_e32 v228, v228, v229
	v_add_f32_e32 v230, v230, v231
	v_add_f32_e32 v232, v232, v233
	v_add_f32_e32 v234, v234, v235
	v_add_f32_e32 v81, 0, v228
	v_add_f32_e32 v81, v81, v230
	v_add_f32_e32 v81, v81, v232
	v_add_f32_e32 v81, v81, v234
	ds_read_b128 v[212:215], v56 offset:12288
	ds_read_b128 v[216:219], v56 offset:13312
	ds_read_b128 v[220:223], v56 offset:14336
	ds_read_b128 v[224:227], v56 offset:15360
	s_waitcnt lgkmcnt(4)
	v_mul_f32_e32 v228, v29, v197
	v_mul_f32_e32 v229, v27, v199
	v_mul_f32_e32 v230, v33, v201
	v_mul_f32_e32 v231, v31, v203
	v_mul_f32_e32 v232, v41, v205
	v_mul_f32_e32 v233, v39, v207
	v_mul_f32_e32 v234, v37, v209
	v_mul_f32_e32 v235, v35, v211
	v_fmac_f32_e32 v228, v28, v196
	v_fmac_f32_e32 v229, v26, v198
	v_fmac_f32_e32 v230, v32, v200
	v_fmac_f32_e32 v231, v30, v202
	v_fmac_f32_e32 v232, v40, v204
	v_fmac_f32_e32 v233, v38, v206
	v_fmac_f32_e32 v234, v36, v208
	v_fmac_f32_e32 v235, v34, v210
	v_add_f32_e32 v228, v228, v229
	v_add_f32_e32 v230, v230, v231
	v_add_f32_e32 v232, v232, v233
	v_add_f32_e32 v234, v234, v235
	v_add_f32_e32 v82, 0, v228
	v_add_f32_e32 v82, v82, v230
	v_add_f32_e32 v82, v82, v232
	v_add_f32_e32 v82, v82, v234
	ds_read_b128 v[196:199], v56 offset:16384
	ds_read_b128 v[200:203], v56 offset:17408
	ds_read_b128 v[204:207], v56 offset:18432
	ds_read_b128 v[208:211], v56 offset:19456
	s_waitcnt lgkmcnt(4)
	v_mul_f32_e32 v228, v29, v213
	v_mul_f32_e32 v229, v27, v215
	v_mul_f32_e32 v230, v33, v217
	v_mul_f32_e32 v231, v31, v219
	v_mul_f32_e32 v232, v41, v221
	v_mul_f32_e32 v233, v39, v223
	v_mul_f32_e32 v234, v37, v225
	v_mul_f32_e32 v235, v35, v227
	v_fmac_f32_e32 v228, v28, v212
	v_fmac_f32_e32 v229, v26, v214
	v_fmac_f32_e32 v230, v32, v216
	v_fmac_f32_e32 v231, v30, v218
	v_fmac_f32_e32 v232, v40, v220
	v_fmac_f32_e32 v233, v38, v222
	v_fmac_f32_e32 v234, v36, v224
	v_fmac_f32_e32 v235, v34, v226
	v_add_f32_e32 v228, v228, v229
	v_add_f32_e32 v230, v230, v231
	v_add_f32_e32 v232, v232, v233
	v_add_f32_e32 v234, v234, v235
	v_add_f32_e32 v83, 0, v228
	v_add_f32_e32 v83, v83, v230
	v_add_f32_e32 v83, v83, v232
	v_add_f32_e32 v83, v83, v234
	ds_read_b128 v[212:215], v56 offset:20480
	ds_read_b128 v[216:219], v56 offset:21504
	ds_read_b128 v[220:223], v56 offset:22528
	ds_read_b128 v[224:227], v56 offset:23552
	s_waitcnt lgkmcnt(4)
	v_mul_f32_e32 v228, v29, v197
	v_mul_f32_e32 v229, v27, v199
	v_mul_f32_e32 v230, v33, v201
	v_mul_f32_e32 v231, v31, v203
	v_mul_f32_e32 v232, v41, v205
	v_mul_f32_e32 v233, v39, v207
	v_mul_f32_e32 v234, v37, v209
	v_mul_f32_e32 v235, v35, v211
	v_fmac_f32_e32 v228, v28, v196
	v_fmac_f32_e32 v229, v26, v198
	v_fmac_f32_e32 v230, v32, v200
	v_fmac_f32_e32 v231, v30, v202
	v_fmac_f32_e32 v232, v40, v204
	v_fmac_f32_e32 v233, v38, v206
	v_fmac_f32_e32 v234, v36, v208
	v_fmac_f32_e32 v235, v34, v210
	v_add_f32_e32 v228, v228, v229
	v_add_f32_e32 v230, v230, v231
	v_add_f32_e32 v232, v232, v233
	v_add_f32_e32 v234, v234, v235
	v_add_f32_e32 v84, 0, v228
	v_add_f32_e32 v84, v84, v230
	v_add_f32_e32 v84, v84, v232
	v_add_f32_e32 v84, v84, v234
	ds_read_b128 v[196:199], v56 offset:24576
	ds_read_b128 v[200:203], v56 offset:25600
	ds_read_b128 v[204:207], v56 offset:26624
	ds_read_b128 v[208:211], v56 offset:27648
	s_waitcnt lgkmcnt(4)
	v_mul_f32_e32 v228, v29, v213
	v_mul_f32_e32 v229, v27, v215
	v_mul_f32_e32 v230, v33, v217
	v_mul_f32_e32 v231, v31, v219
	v_mul_f32_e32 v232, v41, v221
	v_mul_f32_e32 v233, v39, v223
	v_mul_f32_e32 v234, v37, v225
	v_mul_f32_e32 v235, v35, v227
	v_fmac_f32_e32 v228, v28, v212
	v_fmac_f32_e32 v229, v26, v214
	v_fmac_f32_e32 v230, v32, v216
	v_fmac_f32_e32 v231, v30, v218
	v_fmac_f32_e32 v232, v40, v220
	v_fmac_f32_e32 v233, v38, v222
	v_fmac_f32_e32 v234, v36, v224
	v_fmac_f32_e32 v235, v34, v226
	v_add_f32_e32 v228, v228, v229
	v_add_f32_e32 v230, v230, v231
	v_add_f32_e32 v232, v232, v233
	v_add_f32_e32 v234, v234, v235
	v_add_f32_e32 v85, 0, v228
	v_add_f32_e32 v85, v85, v230
	v_add_f32_e32 v85, v85, v232
	v_add_f32_e32 v85, v85, v234
	ds_read_b128 v[212:215], v56 offset:28672
	ds_read_b128 v[216:219], v56 offset:29696
	ds_read_b128 v[220:223], v56 offset:30720
	ds_read_b128 v[224:227], v56 offset:31744
	s_waitcnt lgkmcnt(4)
	v_mul_f32_e32 v228, v29, v197
	v_mul_f32_e32 v229, v27, v199
	v_mul_f32_e32 v230, v33, v201
	v_mul_f32_e32 v231, v31, v203
	v_mul_f32_e32 v232, v41, v205
	v_mul_f32_e32 v233, v39, v207
	v_mul_f32_e32 v234, v37, v209
	v_mul_f32_e32 v235, v35, v211
	v_fmac_f32_e32 v228, v28, v196
	v_fmac_f32_e32 v229, v26, v198
	v_fmac_f32_e32 v230, v32, v200
	v_fmac_f32_e32 v231, v30, v202
	v_fmac_f32_e32 v232, v40, v204
	v_fmac_f32_e32 v233, v38, v206
	v_fmac_f32_e32 v234, v36, v208
	v_fmac_f32_e32 v235, v34, v210
	v_add_f32_e32 v228, v228, v229
	v_add_f32_e32 v230, v230, v231
	v_add_f32_e32 v232, v232, v233
	v_add_f32_e32 v234, v234, v235
	v_add_f32_e32 v86, 0, v228
	v_add_f32_e32 v86, v86, v230
	v_add_f32_e32 v86, v86, v232
	v_add_f32_e32 v86, v86, v234
	ds_read_b128 v[196:199], v56 offset:32768
	ds_read_b128 v[200:203], v56 offset:33792
	ds_read_b128 v[204:207], v56 offset:34816
	ds_read_b128 v[208:211], v56 offset:35840
	s_waitcnt lgkmcnt(4)
	v_mul_f32_e32 v228, v29, v213
	v_mul_f32_e32 v229, v27, v215
	v_mul_f32_e32 v230, v33, v217
	v_mul_f32_e32 v231, v31, v219
	v_mul_f32_e32 v232, v41, v221
	v_mul_f32_e32 v233, v39, v223
	v_mul_f32_e32 v234, v37, v225
	v_mul_f32_e32 v235, v35, v227
	v_fmac_f32_e32 v228, v28, v212
	v_fmac_f32_e32 v229, v26, v214
	v_fmac_f32_e32 v230, v32, v216
	v_fmac_f32_e32 v231, v30, v218
	v_fmac_f32_e32 v232, v40, v220
	v_fmac_f32_e32 v233, v38, v222
	v_fmac_f32_e32 v234, v36, v224
	v_fmac_f32_e32 v235, v34, v226
	v_add_f32_e32 v228, v228, v229
	v_add_f32_e32 v230, v230, v231
	v_add_f32_e32 v232, v232, v233
	v_add_f32_e32 v234, v234, v235
	v_add_f32_e32 v87, 0, v228
	v_add_f32_e32 v87, v87, v230
	v_add_f32_e32 v87, v87, v232
	v_add_f32_e32 v87, v87, v234
	ds_read_b128 v[212:215], v56 offset:36864
	ds_read_b128 v[216:219], v56 offset:37888
	ds_read_b128 v[220:223], v56 offset:38912
	ds_read_b128 v[224:227], v56 offset:39936
	s_waitcnt lgkmcnt(4)
	v_mul_f32_e32 v228, v29, v197
	v_mul_f32_e32 v229, v27, v199
	v_mul_f32_e32 v230, v33, v201
	v_mul_f32_e32 v231, v31, v203
	v_mul_f32_e32 v232, v41, v205
	v_mul_f32_e32 v233, v39, v207
	v_mul_f32_e32 v234, v37, v209
	v_mul_f32_e32 v235, v35, v211
	v_fmac_f32_e32 v228, v28, v196
	v_fmac_f32_e32 v229, v26, v198
	v_fmac_f32_e32 v230, v32, v200
	v_fmac_f32_e32 v231, v30, v202
	v_fmac_f32_e32 v232, v40, v204
	v_fmac_f32_e32 v233, v38, v206
	v_fmac_f32_e32 v234, v36, v208
	v_fmac_f32_e32 v235, v34, v210
	v_add_f32_e32 v228, v228, v229
	v_add_f32_e32 v230, v230, v231
	v_add_f32_e32 v232, v232, v233
	v_add_f32_e32 v234, v234, v235
	v_add_f32_e32 v88, 0, v228
	v_add_f32_e32 v88, v88, v230
	v_add_f32_e32 v88, v88, v232
	v_add_f32_e32 v88, v88, v234
	ds_read_b128 v[196:199], v56 offset:40960
	ds_read_b128 v[200:203], v56 offset:41984
	ds_read_b128 v[204:207], v56 offset:43008
	ds_read_b128 v[208:211], v56 offset:44032
	s_waitcnt lgkmcnt(4)
	v_mul_f32_e32 v228, v29, v213
	v_mul_f32_e32 v229, v27, v215
	v_mul_f32_e32 v230, v33, v217
	v_mul_f32_e32 v231, v31, v219
	v_mul_f32_e32 v232, v41, v221
	v_mul_f32_e32 v233, v39, v223
	v_mul_f32_e32 v234, v37, v225
	v_mul_f32_e32 v235, v35, v227
	v_fmac_f32_e32 v228, v28, v212
	v_fmac_f32_e32 v229, v26, v214
	v_fmac_f32_e32 v230, v32, v216
	v_fmac_f32_e32 v231, v30, v218
	v_fmac_f32_e32 v232, v40, v220
	v_fmac_f32_e32 v233, v38, v222
	v_fmac_f32_e32 v234, v36, v224
	v_fmac_f32_e32 v235, v34, v226
	v_add_f32_e32 v228, v228, v229
	v_add_f32_e32 v230, v230, v231
	v_add_f32_e32 v232, v232, v233
	v_add_f32_e32 v234, v234, v235
	v_add_f32_e32 v89, 0, v228
	v_add_f32_e32 v89, v89, v230
	v_add_f32_e32 v89, v89, v232
	v_add_f32_e32 v89, v89, v234
	ds_read_b128 v[212:215], v56 offset:45056
	ds_read_b128 v[216:219], v56 offset:46080
	ds_read_b128 v[220:223], v56 offset:47104
	ds_read_b128 v[224:227], v56 offset:48128
	s_waitcnt lgkmcnt(4)
	v_mul_f32_e32 v228, v29, v197
	v_mul_f32_e32 v229, v27, v199
	v_mul_f32_e32 v230, v33, v201
	v_mul_f32_e32 v231, v31, v203
	v_mul_f32_e32 v232, v41, v205
	v_mul_f32_e32 v233, v39, v207
	v_mul_f32_e32 v234, v37, v209
	v_mul_f32_e32 v235, v35, v211
	v_fmac_f32_e32 v228, v28, v196
	v_fmac_f32_e32 v229, v26, v198
	v_fmac_f32_e32 v230, v32, v200
	v_fmac_f32_e32 v231, v30, v202
	v_fmac_f32_e32 v232, v40, v204
	v_fmac_f32_e32 v233, v38, v206
	v_fmac_f32_e32 v234, v36, v208
	v_fmac_f32_e32 v235, v34, v210
	v_add_f32_e32 v228, v228, v229
	v_add_f32_e32 v230, v230, v231
	v_add_f32_e32 v232, v232, v233
	v_add_f32_e32 v234, v234, v235
	v_add_f32_e32 v90, 0, v228
	v_add_f32_e32 v90, v90, v230
	v_add_f32_e32 v90, v90, v232
	v_add_f32_e32 v90, v90, v234
	ds_read_b128 v[196:199], v56 offset:49152
	ds_read_b128 v[200:203], v56 offset:50176
	ds_read_b128 v[204:207], v56 offset:51200
	ds_read_b128 v[208:211], v56 offset:52224
	s_waitcnt lgkmcnt(4)
	v_mul_f32_e32 v228, v29, v213
	v_mul_f32_e32 v229, v27, v215
	v_mul_f32_e32 v230, v33, v217
	v_mul_f32_e32 v231, v31, v219
	v_mul_f32_e32 v232, v41, v221
	v_mul_f32_e32 v233, v39, v223
	v_mul_f32_e32 v234, v37, v225
	v_mul_f32_e32 v235, v35, v227
	v_fmac_f32_e32 v228, v28, v212
	v_fmac_f32_e32 v229, v26, v214
	v_fmac_f32_e32 v230, v32, v216
	v_fmac_f32_e32 v231, v30, v218
	v_fmac_f32_e32 v232, v40, v220
	v_fmac_f32_e32 v233, v38, v222
	v_fmac_f32_e32 v234, v36, v224
	v_fmac_f32_e32 v235, v34, v226
	v_add_f32_e32 v228, v228, v229
	v_add_f32_e32 v230, v230, v231
	v_add_f32_e32 v232, v232, v233
	v_add_f32_e32 v234, v234, v235
	v_add_f32_e32 v91, 0, v228
	v_add_f32_e32 v91, v91, v230
	v_add_f32_e32 v91, v91, v232
	v_add_f32_e32 v91, v91, v234
	ds_read_b128 v[212:215], v56 offset:53248
	ds_read_b128 v[216:219], v56 offset:54272
	ds_read_b128 v[220:223], v56 offset:55296
	ds_read_b128 v[224:227], v56 offset:56320
	s_waitcnt lgkmcnt(4)
	v_mul_f32_e32 v228, v29, v197
	v_mul_f32_e32 v229, v27, v199
	v_mul_f32_e32 v230, v33, v201
	v_mul_f32_e32 v231, v31, v203
	v_mul_f32_e32 v232, v41, v205
	v_mul_f32_e32 v233, v39, v207
	v_mul_f32_e32 v234, v37, v209
	v_mul_f32_e32 v235, v35, v211
	v_fmac_f32_e32 v228, v28, v196
	v_fmac_f32_e32 v229, v26, v198
	v_fmac_f32_e32 v230, v32, v200
	v_fmac_f32_e32 v231, v30, v202
	v_fmac_f32_e32 v232, v40, v204
	v_fmac_f32_e32 v233, v38, v206
	v_fmac_f32_e32 v234, v36, v208
	v_fmac_f32_e32 v235, v34, v210
	v_add_f32_e32 v228, v228, v229
	v_add_f32_e32 v230, v230, v231
	v_add_f32_e32 v232, v232, v233
	v_add_f32_e32 v234, v234, v235
	v_add_f32_e32 v92, 0, v228
	v_add_f32_e32 v92, v92, v230
	v_add_f32_e32 v92, v92, v232
	v_add_f32_e32 v92, v92, v234
	ds_read_b128 v[196:199], v56 offset:57344
	ds_read_b128 v[200:203], v56 offset:58368
	ds_read_b128 v[204:207], v56 offset:59392
	ds_read_b128 v[208:211], v56 offset:60416
	s_waitcnt lgkmcnt(4)
	v_mul_f32_e32 v228, v29, v213
	v_mul_f32_e32 v229, v27, v215
	v_mul_f32_e32 v230, v33, v217
	v_mul_f32_e32 v231, v31, v219
	v_mul_f32_e32 v232, v41, v221
	v_mul_f32_e32 v233, v39, v223
	v_mul_f32_e32 v234, v37, v225
	v_mul_f32_e32 v235, v35, v227
	v_fmac_f32_e32 v228, v28, v212
	v_fmac_f32_e32 v229, v26, v214
	v_fmac_f32_e32 v230, v32, v216
	v_fmac_f32_e32 v231, v30, v218
	v_fmac_f32_e32 v232, v40, v220
	v_fmac_f32_e32 v233, v38, v222
	v_fmac_f32_e32 v234, v36, v224
	v_fmac_f32_e32 v235, v34, v226
	v_add_f32_e32 v228, v228, v229
	v_add_f32_e32 v230, v230, v231
	v_add_f32_e32 v232, v232, v233
	v_add_f32_e32 v234, v234, v235
	v_add_f32_e32 v93, 0, v228
	v_add_f32_e32 v93, v93, v230
	v_add_f32_e32 v93, v93, v232
	v_add_f32_e32 v93, v93, v234
	ds_read_b128 v[212:215], v56 offset:61440
	ds_read_b128 v[216:219], v56 offset:62464
	ds_read_b128 v[220:223], v56 offset:63488
	ds_read_b128 v[224:227], v56 offset:64512
	s_waitcnt lgkmcnt(4)
	v_mul_f32_e32 v228, v29, v197
	v_mul_f32_e32 v229, v27, v199
	v_mul_f32_e32 v230, v33, v201
	v_mul_f32_e32 v231, v31, v203
	v_mul_f32_e32 v232, v41, v205
	v_mul_f32_e32 v233, v39, v207
	v_mul_f32_e32 v234, v37, v209
	v_mul_f32_e32 v235, v35, v211
	v_fmac_f32_e32 v228, v28, v196
	v_fmac_f32_e32 v229, v26, v198
	v_fmac_f32_e32 v230, v32, v200
	v_fmac_f32_e32 v231, v30, v202
	v_fmac_f32_e32 v232, v40, v204
	v_fmac_f32_e32 v233, v38, v206
	v_fmac_f32_e32 v234, v36, v208
	v_fmac_f32_e32 v235, v34, v210
	v_add_f32_e32 v228, v228, v229
	v_add_f32_e32 v230, v230, v231
	v_add_f32_e32 v232, v232, v233
	v_add_f32_e32 v234, v234, v235
	v_add_f32_e32 v94, 0, v228
	v_add_f32_e32 v94, v94, v230
	v_add_f32_e32 v94, v94, v232
	v_add_f32_e32 v94, v94, v234
	s_waitcnt lgkmcnt(0)
	v_mul_f32_e32 v228, v29, v213
	v_mul_f32_e32 v229, v27, v215
	v_mul_f32_e32 v230, v33, v217
	v_mul_f32_e32 v231, v31, v219
	v_mul_f32_e32 v232, v41, v221
	v_mul_f32_e32 v233, v39, v223
	v_mul_f32_e32 v234, v37, v225
	v_mul_f32_e32 v235, v35, v227
	v_fmac_f32_e32 v228, v28, v212
	v_fmac_f32_e32 v229, v26, v214
	v_fmac_f32_e32 v230, v32, v216
	v_fmac_f32_e32 v231, v30, v218
	v_fmac_f32_e32 v232, v40, v220
	v_fmac_f32_e32 v233, v38, v222
	v_fmac_f32_e32 v234, v36, v224
	v_fmac_f32_e32 v235, v34, v226
	v_add_f32_e32 v228, v228, v229
	v_add_f32_e32 v230, v230, v231
	v_add_f32_e32 v232, v232, v233
	v_add_f32_e32 v234, v234, v235
	v_add_f32_e32 v95, 0, v228
	v_add_f32_e32 v95, v95, v230
	v_add_f32_e32 v95, v95, v232
	v_add_f32_e32 v95, v95, v234
	v_permlane32_swap_b32_e32 v80, v88
	v_permlane32_swap_b32_e32 v81, v89
	v_permlane32_swap_b32_e32 v82, v90
	v_permlane32_swap_b32_e32 v83, v91
	v_permlane32_swap_b32_e32 v84, v92
	v_permlane32_swap_b32_e32 v85, v93
	v_permlane32_swap_b32_e32 v86, v94
	v_permlane32_swap_b32_e32 v87, v95
	v_add_f32_e32 v80, v80, v88
	v_add_f32_e32 v81, v81, v89
	v_add_f32_e32 v82, v82, v90
	v_add_f32_e32 v83, v83, v91
	v_add_f32_e32 v84, v84, v92
	v_add_f32_e32 v85, v85, v93
	v_add_f32_e32 v86, v86, v94
	v_add_f32_e32 v87, v87, v95
	v_permlane16_swap_b32_e32 v80, v84
	v_permlane16_swap_b32_e32 v81, v85
	v_permlane16_swap_b32_e32 v82, v86
	v_permlane16_swap_b32_e32 v83, v87
	v_add_f32_e32 v88, v80, v84
	v_add_f32_e32 v89, v81, v85
	v_add_f32_e32 v90, v82, v86
	v_add_f32_e32 v91, v83, v87
	v_add_f32_dpp v88, v88, v88 row_ror:8 row_mask:0xf bank_mask:0xf
	v_add_f32_dpp v89, v89, v89 row_ror:8 row_mask:0xf bank_mask:0xf
	v_add_f32_dpp v90, v90, v90 row_ror:8 row_mask:0xf bank_mask:0xf
	v_add_f32_dpp v91, v91, v91 row_ror:8 row_mask:0xf bank_mask:0xf
	v_add_f32_dpp v88, v88, v88 row_ror:4 row_mask:0xf bank_mask:0xf
	v_add_f32_dpp v89, v89, v89 row_ror:4 row_mask:0xf bank_mask:0xf
	v_add_f32_dpp v90, v90, v90 row_ror:4 row_mask:0xf bank_mask:0xf
	v_add_f32_dpp v91, v91, v91 row_ror:4 row_mask:0xf bank_mask:0xf
	v_add_f32_dpp v88, v88, v88 quad_perm:[2,3,0,1] row_mask:0xf bank_mask:0xf
	v_add_f32_dpp v89, v89, v89 quad_perm:[2,3,0,1] row_mask:0xf bank_mask:0xf
	v_add_f32_dpp v90, v90, v90 quad_perm:[2,3,0,1] row_mask:0xf bank_mask:0xf
	v_add_f32_dpp v91, v91, v91 quad_perm:[2,3,0,1] row_mask:0xf bank_mask:0xf
	v_add_f32_dpp v88, v88, v88 quad_perm:[1,0,3,2] row_mask:0xf bank_mask:0xf
	v_add_f32_dpp v89, v89, v89 quad_perm:[1,0,3,2] row_mask:0xf bank_mask:0xf
	v_add_f32_dpp v90, v90, v90 quad_perm:[1,0,3,2] row_mask:0xf bank_mask:0xf
	v_add_f32_dpp v91, v91, v91 quad_perm:[1,0,3,2] row_mask:0xf bank_mask:0xf
	s_mov_b32 vcc_lo, 0xaaaaaaaa
	s_mov_b32 vcc_hi, 0xaaaaaaaa
	v_cndmask_b32_e32 v92, v88, v89, vcc
	v_cndmask_b32_e32 v93, v90, v91, vcc
	s_mov_b32 vcc_lo, 0xcccccccc
	s_mov_b32 vcc_hi, 0xcccccccc
	v_cndmask_b32_e32 v92, v92, v93, vcc
	ds_bpermute_b32 v26, v97, v92
	s_waitcnt lgkmcnt(0)
	s_and_saveexec_b64 s[0:1], s[4:5]
	s_cbranch_execz .LBB0_693
	s_mov_b32 s2, 0xbfb8aa3b
	v_add_f32_e32 v26, v26, v99
	v_mul_f32_e64 v27, |v26|, s2
	v_exp_f32_e32 v27, v27
	v_min_f32_e32 v26, 0, v26
	v_add_f32_e32 v27, 1.0, v27
	v_log_f32_e32 v27, v27
	s_nop 0
	v_fmac_f32_e32 v26, 0xbf317218, v27
	global_store_dword v[16:17], v26, off
	s_branch .LBB0_693
